# G1 input projection: rotate the column panel (u/q/k/v class) a workgroup takes by two per round so every workgroup gets one epilogue of each class (balances the q/k norm epilogues)
# speedup vs baseline: 1.0703x; 1.0058x over previous
.LBB0_353:
	s_ashr_i32 s7, s7, 3
	s_add_i32 s7, s36, s7
	s_ashr_i32 s12, s7, 31
	s_lshr_b32 s12, s12, 28
	s_add_i32 s12, s7, s12
	s_ashr_i32 s30, s12, 4
	s_lshl_b32 s31, s30, 1
	s_sub_i32 s30, 0x80, s31
	s_min_i32 s36, s30, 2
	s_abs_i32 s30, s36
	v_cvt_f32_u32_e32 v0, s30
	s_sub_i32 s38, 0, s30
	s_and_b32 s12, s12, -16
	s_sub_i32 s7, s7, s12
	v_rcp_iflag_f32_e32 v0, v0
	s_abs_i32 s12, s7
	s_xor_b32 s37, s7, s36
	s_ashr_i32 s37, s37, 31
	v_mul_f32_e32 v0, 0x4f7ffffe, v0
	v_cvt_u32_f32_e32 v0, v0
	s_nop 0
	v_readfirstlane_b32 s39, v0
	s_mul_i32 s38, s38, s39
	s_mul_hi_u32 s38, s39, s38
	s_add_i32 s39, s39, s38
	s_mul_hi_u32 s38, s12, s39
	s_mul_i32 s39, s38, s30
	s_sub_i32 s12, s12, s39
	s_add_i32 s40, s38, 1
	s_sub_i32 s39, s12, s30
	s_cmp_ge_u32 s12, s30
	s_cselect_b32 s38, s40, s38
	s_cselect_b32 s12, s39, s12
	s_add_i32 s39, s38, 1
	s_cmp_ge_u32 s12, s30
	s_cselect_b32 s12, s39, s38
	s_xor_b32 s12, s12, s37
	s_sub_i32 s30, s12, s37
	s_mul_i32 s12, s30, s36
	s_sub_i32 s7, s7, s12
	s_add_i32 s36, s31, s7
	s_lshl_b32 s12, s78, 1
	s_add_i32 s30, s30, s12
	s_and_b32 s30, s30, 7
	s_mov_b64 s[40:41], -1
